# hand-written prep_conv as static wave tasks (lane = channel, 5-tap window sliding in registers, all rows of the half loaded up front); sp2 queue keeps only prep_dt
# speedup vs baseline: 1.0160x; 1.0160x over previous
.Lcv_entry:
	v_lshrrev_b32_e32 v52, 6, v206
	v_and_b32_e32 v30, 63, v206
	v_readfirstlane_b32 s40, v52
	s_cmp_ge_u32 s40, 6
	s_cbranch_scc1 .Ls5l_back
	s_mul_i32 s41, s63, 6
	s_add_u32 s41, s41, s40
	s_lshr_b32 s42, s41, 5
	s_bfe_u32 s43, s41, 0x10004
	s_and_b32 s44, s41, 15
	s_lshl_b32 s45, s42, 7
	s_cmp_lt_u32 s42, 32
	s_cbranch_scc0 .Lcv_lat
	s_lshr_b32 s46, s42, 1
	s_lshl_b32 s46, s46, 8
	s_add_u32 s47, s46, 0x100
	s_branch .Lcv_seq
.Lcv_lat:
	s_sub_u32 s46, s42, 32
	s_lshr_b32 s46, s46, 3
	s_lshl_b32 s46, s46, 10
	s_add_u32 s46, s46, 0x1000
	s_add_u32 s47, s46, 0x400
.Lcv_seq:
	s_cmp_lg_u32 s45, s46
	s_cselect_b32 s48, -1, 0
	s_cmp_lg_u32 s43, 0
	s_cselect_b32 s48, -1, s48
	s_add_u32 s49, s45, 0x80
	s_cmp_lg_u32 s49, s47
	s_cselect_b32 s49, -1, 0
	s_cmp_lg_u32 s43, 1
	s_cselect_b32 s49, -1, s49
	s_lshl_b32 s50, s43, 6
	s_add_u32 s50, s50, s45
	s_sub_u32 s50, s50, 2
	s_mul_i32 s50, s50, 0x2440
	s_lshl_b32 s51, s44, 8
	s_add_u32 s50, s50, s51
	s_add_u32 s50, s50, 0x3a24800
	s_add_u32 s52, s96, s50
	s_addc_u32 s53, s97, 0
	v_lshlrev_b32_e32 v31, 2, v30
	v_readlane_b32 s54, v237, 17
	v_readlane_b32 s55, v237, 18
	s_mul_i32 s50, s36, 0x5000
	s_add_u32 s50, s50, s51
	s_add_u32 s54, s54, s50
	s_addc_u32 s55, s55, 0
	global_load_dword v24, v31, s[54:55]
	s_add_u32 s54, s54, 0x1000
	s_addc_u32 s55, s55, 0
	global_load_dword v25, v31, s[54:55]
	s_add_u32 s54, s54, 0x1000
	s_addc_u32 s55, s55, 0
	global_load_dword v26, v31, s[54:55]
	s_add_u32 s54, s54, 0x1000
	s_addc_u32 s55, s55, 0
	global_load_dword v27, v31, s[54:55]
	s_add_u32 s54, s54, 0x1000
	s_addc_u32 s55, s55, 0
	global_load_dword v28, v31, s[54:55]
	v_readlane_b32 s54, v237, 19
	v_readlane_b32 s55, v237, 20
	s_lshl_b32 s50, s36, 12
	s_add_u32 s50, s50, s51
	s_add_u32 s54, s54, s50
	s_addc_u32 s55, s55, 0
	global_load_dword v29, v31, s[54:55]
	global_load_dword v4, v31, s[52:53]
	s_add_u32 s52, s52, 0x2440
	s_addc_u32 s53, s53, 0
	global_load_dword v5, v31, s[52:53]
	s_add_u32 s52, s52, 0x2440
	s_addc_u32 s53, s53, 0
	global_load_dword v6, v31, s[52:53]
	s_add_u32 s52, s52, 0x2440
	s_addc_u32 s53, s53, 0
	global_load_dword v7, v31, s[52:53]
	s_add_u32 s52, s52, 0x2440
	s_addc_u32 s53, s53, 0
	global_load_dword v8, v31, s[52:53]
	s_add_u32 s52, s52, 0x2440
	s_addc_u32 s53, s53, 0
	global_load_dword v9, v31, s[52:53]
	s_add_u32 s52, s52, 0x2440
	s_addc_u32 s53, s53, 0
	global_load_dword v10, v31, s[52:53]
	s_add_u32 s52, s52, 0x2440
	s_addc_u32 s53, s53, 0
	global_load_dword v11, v31, s[52:53]
	s_add_u32 s52, s52, 0x2440
	s_addc_u32 s53, s53, 0
	global_load_dword v12, v31, s[52:53]
	s_add_u32 s52, s52, 0x2440
	s_addc_u32 s53, s53, 0
	global_load_dword v13, v31, s[52:53]
	s_add_u32 s52, s52, 0x2440
	s_addc_u32 s53, s53, 0
	global_load_dword v14, v31, s[52:53]
	s_add_u32 s52, s52, 0x2440
	s_addc_u32 s53, s53, 0
	global_load_dword v15, v31, s[52:53]
	s_add_u32 s52, s52, 0x2440
	s_addc_u32 s53, s53, 0
	global_load_dword v70, v31, s[52:53]
	s_add_u32 s52, s52, 0x2440
	s_addc_u32 s53, s53, 0
	global_load_dword v71, v31, s[52:53]
	s_add_u32 s52, s52, 0x2440
	s_addc_u32 s53, s53, 0
	global_load_dword v72, v31, s[52:53]
	s_add_u32 s52, s52, 0x2440
	s_addc_u32 s53, s53, 0
	global_load_dword v73, v31, s[52:53]
	s_add_u32 s52, s52, 0x2440
	s_addc_u32 s53, s53, 0
	global_load_dword v74, v31, s[52:53]
	s_add_u32 s52, s52, 0x2440
	s_addc_u32 s53, s53, 0
	global_load_dword v75, v31, s[52:53]
	s_add_u32 s52, s52, 0x2440
	s_addc_u32 s53, s53, 0
	global_load_dword v76, v31, s[52:53]
	s_add_u32 s52, s52, 0x2440
	s_addc_u32 s53, s53, 0
	global_load_dword v77, v31, s[52:53]
	s_add_u32 s52, s52, 0x2440
	s_addc_u32 s53, s53, 0
	global_load_dword v78, v31, s[52:53]
	s_add_u32 s52, s52, 0x2440
	s_addc_u32 s53, s53, 0
	global_load_dword v79, v31, s[52:53]
	s_add_u32 s52, s52, 0x2440
	s_addc_u32 s53, s53, 0
	global_load_dword v80, v31, s[52:53]
	s_add_u32 s52, s52, 0x2440
	s_addc_u32 s53, s53, 0
	global_load_dword v81, v31, s[52:53]
	s_add_u32 s52, s52, 0x2440
	s_addc_u32 s53, s53, 0
	global_load_dword v82, v31, s[52:53]
	s_add_u32 s52, s52, 0x2440
	s_addc_u32 s53, s53, 0
	global_load_dword v83, v31, s[52:53]
	s_add_u32 s52, s52, 0x2440
	s_addc_u32 s53, s53, 0
	global_load_dword v84, v31, s[52:53]
	s_add_u32 s52, s52, 0x2440
	s_addc_u32 s53, s53, 0
	global_load_dword v85, v31, s[52:53]
	s_add_u32 s52, s52, 0x2440
	s_addc_u32 s53, s53, 0
	global_load_dword v86, v31, s[52:53]
	s_add_u32 s52, s52, 0x2440
	s_addc_u32 s53, s53, 0
	global_load_dword v87, v31, s[52:53]
	s_add_u32 s52, s52, 0x2440
	s_addc_u32 s53, s53, 0
	global_load_dword v88, v31, s[52:53]
	s_add_u32 s52, s52, 0x2440
	s_addc_u32 s53, s53, 0
	global_load_dword v89, v31, s[52:53]
	s_add_u32 s52, s52, 0x2440
	s_addc_u32 s53, s53, 0
	global_load_dword v90, v31, s[52:53]
	s_add_u32 s52, s52, 0x2440
	s_addc_u32 s53, s53, 0
	global_load_dword v91, v31, s[52:53]
	s_add_u32 s52, s52, 0x2440
	s_addc_u32 s53, s53, 0
	global_load_dword v92, v31, s[52:53]
	s_add_u32 s52, s52, 0x2440
	s_addc_u32 s53, s53, 0
	global_load_dword v93, v31, s[52:53]
	s_add_u32 s52, s52, 0x2440
	s_addc_u32 s53, s53, 0
	global_load_dword v94, v31, s[52:53]
	s_add_u32 s52, s52, 0x2440
	s_addc_u32 s53, s53, 0
	global_load_dword v95, v31, s[52:53]
	s_add_u32 s52, s52, 0x2440
	s_addc_u32 s53, s53, 0
	global_load_dword v96, v31, s[52:53]
	s_add_u32 s52, s52, 0x2440
	s_addc_u32 s53, s53, 0
	global_load_dword v97, v31, s[52:53]
	s_add_u32 s52, s52, 0x2440
	s_addc_u32 s53, s53, 0
	global_load_dword v98, v31, s[52:53]
	s_add_u32 s52, s52, 0x2440
	s_addc_u32 s53, s53, 0
	global_load_dword v99, v31, s[52:53]
	s_add_u32 s52, s52, 0x2440
	s_addc_u32 s53, s53, 0
	global_load_dword v100, v31, s[52:53]
	s_add_u32 s52, s52, 0x2440
	s_addc_u32 s53, s53, 0
	global_load_dword v101, v31, s[52:53]
	s_add_u32 s52, s52, 0x2440
	s_addc_u32 s53, s53, 0
	global_load_dword v102, v31, s[52:53]
	s_add_u32 s52, s52, 0x2440
	s_addc_u32 s53, s53, 0
	global_load_dword v103, v31, s[52:53]
	s_add_u32 s52, s52, 0x2440
	s_addc_u32 s53, s53, 0
	global_load_dword v104, v31, s[52:53]
	s_add_u32 s52, s52, 0x2440
	s_addc_u32 s53, s53, 0
	global_load_dword v105, v31, s[52:53]
	s_add_u32 s52, s52, 0x2440
	s_addc_u32 s53, s53, 0
	global_load_dword v106, v31, s[52:53]
	s_add_u32 s52, s52, 0x2440
	s_addc_u32 s53, s53, 0
	global_load_dword v107, v31, s[52:53]
	s_add_u32 s52, s52, 0x2440
	s_addc_u32 s53, s53, 0
	global_load_dword v108, v31, s[52:53]
	s_add_u32 s52, s52, 0x2440
	s_addc_u32 s53, s53, 0
	global_load_dword v109, v31, s[52:53]
	s_add_u32 s52, s52, 0x2440
	s_addc_u32 s53, s53, 0
	global_load_dword v110, v31, s[52:53]
	s_add_u32 s52, s52, 0x2440
	s_addc_u32 s53, s53, 0
	global_load_dword v111, v31, s[52:53]
	s_add_u32 s52, s52, 0x2440
	s_addc_u32 s53, s53, 0
	global_load_dword v112, v31, s[52:53]
	s_add_u32 s52, s52, 0x2440
	s_addc_u32 s53, s53, 0
	global_load_dword v113, v31, s[52:53]
	s_add_u32 s52, s52, 0x2440
	s_addc_u32 s53, s53, 0
	global_load_dword v114, v31, s[52:53]
	s_add_u32 s52, s52, 0x2440
	s_addc_u32 s53, s53, 0
	global_load_dword v115, v31, s[52:53]
	s_add_u32 s52, s52, 0x2440
	s_addc_u32 s53, s53, 0
	global_load_dword v116, v31, s[52:53]
	s_add_u32 s52, s52, 0x2440
	s_addc_u32 s53, s53, 0
	global_load_dword v117, v31, s[52:53]
	s_add_u32 s52, s52, 0x2440
	s_addc_u32 s53, s53, 0
	global_load_dword v118, v31, s[52:53]
	s_add_u32 s52, s52, 0x2440
	s_addc_u32 s53, s53, 0
	global_load_dword v119, v31, s[52:53]
	s_add_u32 s52, s52, 0x2440
	s_addc_u32 s53, s53, 0
	global_load_dword v120, v31, s[52:53]
	s_add_u32 s52, s52, 0x2440
	s_addc_u32 s53, s53, 0
	global_load_dword v121, v31, s[52:53]
	s_add_u32 s52, s52, 0x2440
	s_addc_u32 s53, s53, 0
	global_load_dword v122, v31, s[52:53]
	s_add_u32 s52, s52, 0x2440
	s_addc_u32 s53, s53, 0
	global_load_dword v123, v31, s[52:53]
	s_add_u32 s52, s52, 0x2440
	s_addc_u32 s53, s53, 0
	global_load_dword v124, v31, s[52:53]
	s_add_u32 s52, s52, 0x2440
	s_addc_u32 s53, s53, 0
	global_load_dword v125, v31, s[52:53]
	s_add_u32 s52, s52, 0x2440
	s_addc_u32 s53, s53, 0
	s_cmp_lt_u32 s44, 8
	s_cbranch_scc0 .Lcv_tb
	s_lshl_b32 s50, s42, 3
	s_add_u32 s50, s50, s44
	s_lshl_b32 s50, s50, 14
	s_add_u32 s50, s50, 0xc184000
	s_branch .Lcv_tj
.Lcv_tb:
	s_sub_u32 s51, s44, 8
	s_lshr_b32 s50, s51, 1
	s_and_b32 s51, s51, 1
	s_lshl_b32 s56, s42, 1
	s_add_u32 s50, s50, s56
	s_lshl_b32 s50, s50, 15
	s_lshl_b32 s51, s51, 14
	s_add_u32 s50, s50, s51
	s_add_u32 s50, s50, 0xbe84000
.Lcv_tj:
	s_lshl_b32 s51, s43, 7
	s_add_u32 s50, s50, s51
	s_add_u32 s56, s96, s50
	s_addc_u32 s57, s97, 0
	v_lshlrev_b32_e32 v32, 8, v30
	s_cmp_lt_u32 s44, 12
	s_cselect_b32 s50, 8, 12
	s_sub_u32 s50, s44, s50
	s_lshl_b32 s50, s50, 7
	s_lshl_b32 s51, s43, 6
	s_add_u32 s51, s51, s45
	s_lshl_b32 s51, s51, 9
	s_add_u32 s50, s50, s51
	s_mov_b32 s51, 0xbb84000
	s_cmp_lt_u32 s44, 12
	s_cselect_b32 s51, 0xb884000, s51
	s_add_u32 s50, s50, s51
	s_add_u32 s58, s96, s50
	s_addc_u32 s59, s97, 0
	v_lshrrev_b32_e32 v52, 3, v30
	v_and_b32_e32 v53, 7, v30
	v_lshlrev_b32_e32 v35, 9, v52
	v_lshl_add_u32 v35, v53, 4, v35
	s_mul_i32 s50, s40, 16896
	v_lshl_add_u32 v33, v30, 1, s50
	v_lshl_add_u32 v34, v30, 4, s50
	s_mov_b32 s50, 0
	s_waitcnt vmcnt(56)
	v_and_b32_e32 v4, s48, v4
	v_and_b32_e32 v5, s48, v5
.Lcv_pass:
	v_fma_f32 v36, v4, v24, v29
	v_fma_f32 v37, v5, v24, v29
	v_fma_f32 v38, v6, v24, v29
	v_fma_f32 v39, v7, v24, v29
	v_fma_f32 v40, v8, v24, v29
	v_fma_f32 v41, v9, v24, v29
	v_fma_f32 v42, v10, v24, v29
	v_fma_f32 v43, v11, v24, v29
	v_fmac_f32_e32 v36, v5, v25
	v_fmac_f32_e32 v37, v6, v25
	v_fmac_f32_e32 v38, v7, v25
	v_fmac_f32_e32 v39, v8, v25
	v_fmac_f32_e32 v40, v9, v25
	v_fmac_f32_e32 v41, v10, v25
	v_fmac_f32_e32 v42, v11, v25
	v_fmac_f32_e32 v43, v12, v25
	v_fmac_f32_e32 v36, v6, v26
	v_fmac_f32_e32 v37, v7, v26
	v_fmac_f32_e32 v38, v8, v26
	v_fmac_f32_e32 v39, v9, v26
	v_fmac_f32_e32 v40, v10, v26
	v_fmac_f32_e32 v41, v11, v26
	v_fmac_f32_e32 v42, v12, v26
	v_fmac_f32_e32 v43, v13, v26
	v_fmac_f32_e32 v36, v7, v27
	v_fmac_f32_e32 v37, v8, v27
	v_fmac_f32_e32 v38, v9, v27
	v_fmac_f32_e32 v39, v10, v27
	v_fmac_f32_e32 v40, v11, v27
	v_fmac_f32_e32 v41, v12, v27
	v_fmac_f32_e32 v42, v13, v27
	v_fmac_f32_e32 v43, v14, v27
	v_fmac_f32_e32 v36, v8, v28
	v_fmac_f32_e32 v37, v9, v28
	v_fmac_f32_e32 v38, v10, v28
	v_fmac_f32_e32 v39, v11, v28
	v_fmac_f32_e32 v40, v12, v28
	v_fmac_f32_e32 v41, v13, v28
	v_fmac_f32_e32 v42, v14, v28
	v_fmac_f32_e32 v43, v15, v28
	v_mul_f32_e32 v44, 0xbfb8aa3b, v36
	v_mul_f32_e32 v45, 0xbfb8aa3b, v37
	v_mul_f32_e32 v46, 0xbfb8aa3b, v38
	v_mul_f32_e32 v47, 0xbfb8aa3b, v39
	v_mul_f32_e32 v48, 0xbfb8aa3b, v40
	v_mul_f32_e32 v49, 0xbfb8aa3b, v41
	v_mul_f32_e32 v50, 0xbfb8aa3b, v42
	v_mul_f32_e32 v51, 0xbfb8aa3b, v43
	v_exp_f32_e32 v44, v44
	v_exp_f32_e32 v45, v45
	v_exp_f32_e32 v46, v46
	v_exp_f32_e32 v47, v47
	v_exp_f32_e32 v48, v48
	v_exp_f32_e32 v49, v49
	v_exp_f32_e32 v50, v50
	v_exp_f32_e32 v51, v51
	v_add_f32_e32 v44, 1.0, v44
	v_add_f32_e32 v45, 1.0, v45
	v_add_f32_e32 v46, 1.0, v46
	v_add_f32_e32 v47, 1.0, v47
	v_add_f32_e32 v48, 1.0, v48
	v_add_f32_e32 v49, 1.0, v49
	v_add_f32_e32 v50, 1.0, v50
	v_add_f32_e32 v51, 1.0, v51
	v_div_scale_f32 v52, s[100:101], v44, v44, v36
	v_rcp_f32_e32 v53, v52
	s_nop 0
	v_fma_f32 v54, -v52, v53, 1.0
	v_fmac_f32_e32 v53, v54, v53
	v_div_scale_f32 v54, vcc, v36, v44, v36
	v_mul_f32_e32 v55, v54, v53
	v_fma_f32 v56, -v52, v55, v54
	v_fmac_f32_e32 v55, v56, v53
	v_fma_f32 v52, -v52, v55, v54
	v_div_fmas_f32 v52, v52, v53, v55
	v_div_fixup_f32 v36, v52, v44, v36
	v_div_scale_f32 v52, s[100:101], v45, v45, v37
	v_rcp_f32_e32 v53, v52
	s_nop 0
	v_fma_f32 v54, -v52, v53, 1.0
	v_fmac_f32_e32 v53, v54, v53
	v_div_scale_f32 v54, vcc, v37, v45, v37
	v_mul_f32_e32 v55, v54, v53
	v_fma_f32 v56, -v52, v55, v54
	v_fmac_f32_e32 v55, v56, v53
	v_fma_f32 v52, -v52, v55, v54
	v_div_fmas_f32 v52, v52, v53, v55
	v_div_fixup_f32 v37, v52, v45, v37
	v_div_scale_f32 v52, s[100:101], v46, v46, v38
	v_rcp_f32_e32 v53, v52
	s_nop 0
	v_fma_f32 v54, -v52, v53, 1.0
	v_fmac_f32_e32 v53, v54, v53
	v_div_scale_f32 v54, vcc, v38, v46, v38
	v_mul_f32_e32 v55, v54, v53
	v_fma_f32 v56, -v52, v55, v54
	v_fmac_f32_e32 v55, v56, v53
	v_fma_f32 v52, -v52, v55, v54
	v_div_fmas_f32 v52, v52, v53, v55
	v_div_fixup_f32 v38, v52, v46, v38
	v_div_scale_f32 v52, s[100:101], v47, v47, v39
	v_rcp_f32_e32 v53, v52
	s_nop 0
	v_fma_f32 v54, -v52, v53, 1.0
	v_fmac_f32_e32 v53, v54, v53
	v_div_scale_f32 v54, vcc, v39, v47, v39
	v_mul_f32_e32 v55, v54, v53
	v_fma_f32 v56, -v52, v55, v54
	v_fmac_f32_e32 v55, v56, v53
	v_fma_f32 v52, -v52, v55, v54
	v_div_fmas_f32 v52, v52, v53, v55
	v_div_fixup_f32 v39, v52, v47, v39
	v_div_scale_f32 v52, s[100:101], v48, v48, v40
	v_rcp_f32_e32 v53, v52
	s_nop 0
	v_fma_f32 v54, -v52, v53, 1.0
	v_fmac_f32_e32 v53, v54, v53
	v_div_scale_f32 v54, vcc, v40, v48, v40
	v_mul_f32_e32 v55, v54, v53
	v_fma_f32 v56, -v52, v55, v54
	v_fmac_f32_e32 v55, v56, v53
	v_fma_f32 v52, -v52, v55, v54
	v_div_fmas_f32 v52, v52, v53, v55
	v_div_fixup_f32 v40, v52, v48, v40
	v_div_scale_f32 v52, s[100:101], v49, v49, v41
	v_rcp_f32_e32 v53, v52
	s_nop 0
	v_fma_f32 v54, -v52, v53, 1.0
	v_fmac_f32_e32 v53, v54, v53
	v_div_scale_f32 v54, vcc, v41, v49, v41
	v_mul_f32_e32 v55, v54, v53
	v_fma_f32 v56, -v52, v55, v54
	v_fmac_f32_e32 v55, v56, v53
	v_fma_f32 v52, -v52, v55, v54
	v_div_fmas_f32 v52, v52, v53, v55
	v_div_fixup_f32 v41, v52, v49, v41
	v_div_scale_f32 v52, s[100:101], v50, v50, v42
	v_rcp_f32_e32 v53, v52
	s_nop 0
	v_fma_f32 v54, -v52, v53, 1.0
	v_fmac_f32_e32 v53, v54, v53
	v_div_scale_f32 v54, vcc, v42, v50, v42
	v_mul_f32_e32 v55, v54, v53
	v_fma_f32 v56, -v52, v55, v54
	v_fmac_f32_e32 v55, v56, v53
	v_fma_f32 v52, -v52, v55, v54
	v_div_fmas_f32 v52, v52, v53, v55
	v_div_fixup_f32 v42, v52, v50, v42
	v_div_scale_f32 v52, s[100:101], v51, v51, v43
	v_rcp_f32_e32 v53, v52
	s_nop 0
	v_fma_f32 v54, -v52, v53, 1.0
	v_fmac_f32_e32 v53, v54, v53
	v_div_scale_f32 v54, vcc, v43, v51, v43
	v_mul_f32_e32 v55, v54, v53
	v_fma_f32 v56, -v52, v55, v54
	v_fmac_f32_e32 v55, v56, v53
	v_fma_f32 v52, -v52, v55, v54
	v_div_fmas_f32 v52, v52, v53, v55
	v_div_fixup_f32 v43, v52, v51, v43
	v_cvt_pk_bf16_f32 v60, v36, v37
	v_cvt_pk_bf16_f32 v61, v38, v39
	v_cvt_pk_bf16_f32 v62, v40, v41
	v_cvt_pk_bf16_f32 v63, v42, v43
	s_cmp_lt_u32 s44, 12
	s_cbranch_scc0 .Lcv_not
	global_store_dwordx4 v32, v[60:63], s[56:57]
	s_add_u32 s56, s56, 16
	s_addc_u32 s57, s57, 0
.Lcv_not:
	s_cmp_lt_u32 s44, 8
	s_cbranch_scc1 .Lcv_nor
	ds_write_b16 v33, v60 offset:0
	ds_write_b16_d16_hi v33, v60 offset:128
	ds_write_b16 v33, v61 offset:256
	ds_write_b16_d16_hi v33, v61 offset:384
	ds_write_b16 v33, v62 offset:512
	ds_write_b16_d16_hi v33, v62 offset:640
	ds_write_b16 v33, v63 offset:768
	ds_write_b16_d16_hi v33, v63 offset:896
	s_waitcnt lgkmcnt(0)
	ds_read_b128 v[64:67], v34
	s_waitcnt lgkmcnt(0)
	global_store_dwordx4 v35, v[64:67], s[58:59]
	s_add_u32 s58, s58, 0x1000
	s_addc_u32 s59, s59, 0
.Lcv_nor:
	s_add_u32 s50, s50, 1
	s_cmp_eq_u32 s50, 8
	s_cbranch_scc1 .Lcv_done
	v_mov_b32_e32 v4, v12
	v_mov_b32_e32 v5, v13
	v_mov_b32_e32 v6, v14
	v_mov_b32_e32 v7, v15
	s_sub_u32 s51, s44, 8
	s_cmp_lt_u32 s51, 4
	s_cselect_b32 s51, 1, 0
	s_cmp_eq_u32 s50, 1
	s_cbranch_scc1 .Lcv_sl1
	s_cmp_eq_u32 s50, 2
	s_cbranch_scc1 .Lcv_sl2
	s_cmp_eq_u32 s50, 3
	s_cbranch_scc1 .Lcv_sl3
	s_cmp_eq_u32 s50, 4
	s_cbranch_scc1 .Lcv_sl4
	s_cmp_eq_u32 s50, 5
	s_cbranch_scc1 .Lcv_sl5
	s_cmp_eq_u32 s50, 6
	s_cbranch_scc1 .Lcv_sl6
	s_cmp_eq_u32 s50, 7
	s_cbranch_scc1 .Lcv_sl7
.Lcv_sl1:
	s_cmp_eq_u32 s51, 1
	s_cbranch_scc1 .Lcv_sl1b
	s_waitcnt vmcnt(49)
	s_branch .Lcv_sl1j
.Lcv_sl1b:
	s_waitcnt vmcnt(50)
.Lcv_sl1j:
	v_mov_b32_e32 v8, v70
	v_mov_b32_e32 v9, v71
	v_mov_b32_e32 v10, v72
	v_mov_b32_e32 v11, v73
	v_mov_b32_e32 v12, v74
	v_mov_b32_e32 v13, v75
	v_mov_b32_e32 v14, v76
	v_mov_b32_e32 v15, v77
	s_branch .Lcv_pass
.Lcv_sl2:
	s_cmp_eq_u32 s51, 1
	s_cbranch_scc1 .Lcv_sl2b
	s_waitcnt vmcnt(42)
	s_branch .Lcv_sl2j
.Lcv_sl2b:
	s_waitcnt vmcnt(44)
.Lcv_sl2j:
	v_mov_b32_e32 v8, v78
	v_mov_b32_e32 v9, v79
	v_mov_b32_e32 v10, v80
	v_mov_b32_e32 v11, v81
	v_mov_b32_e32 v12, v82
	v_mov_b32_e32 v13, v83
	v_mov_b32_e32 v14, v84
	v_mov_b32_e32 v15, v85
	s_branch .Lcv_pass
.Lcv_sl3:
	s_cmp_eq_u32 s51, 1
	s_cbranch_scc1 .Lcv_sl3b
	s_waitcnt vmcnt(35)
	s_branch .Lcv_sl3j
.Lcv_sl3b:
	s_waitcnt vmcnt(38)
.Lcv_sl3j:
	v_mov_b32_e32 v8, v86
	v_mov_b32_e32 v9, v87
	v_mov_b32_e32 v10, v88
	v_mov_b32_e32 v11, v89
	v_mov_b32_e32 v12, v90
	v_mov_b32_e32 v13, v91
	v_mov_b32_e32 v14, v92
	v_mov_b32_e32 v15, v93
	s_branch .Lcv_pass
.Lcv_sl4:
	s_cmp_eq_u32 s51, 1
	s_cbranch_scc1 .Lcv_sl4b
	s_waitcnt vmcnt(28)
	s_branch .Lcv_sl4j
.Lcv_sl4b:
	s_waitcnt vmcnt(32)
.Lcv_sl4j:
	v_mov_b32_e32 v8, v94
	v_mov_b32_e32 v9, v95
	v_mov_b32_e32 v10, v96
	v_mov_b32_e32 v11, v97
	v_mov_b32_e32 v12, v98
	v_mov_b32_e32 v13, v99
	v_mov_b32_e32 v14, v100
	v_mov_b32_e32 v15, v101
	s_branch .Lcv_pass
.Lcv_sl5:
	s_cmp_eq_u32 s51, 1
	s_cbranch_scc1 .Lcv_sl5b
	s_waitcnt vmcnt(21)
	s_branch .Lcv_sl5j
.Lcv_sl5b:
	s_waitcnt vmcnt(26)
.Lcv_sl5j:
	v_mov_b32_e32 v8, v102
	v_mov_b32_e32 v9, v103
	v_mov_b32_e32 v10, v104
	v_mov_b32_e32 v11, v105
	v_mov_b32_e32 v12, v106
	v_mov_b32_e32 v13, v107
	v_mov_b32_e32 v14, v108
	v_mov_b32_e32 v15, v109
	s_branch .Lcv_pass
.Lcv_sl6:
	s_cmp_eq_u32 s51, 1
	s_cbranch_scc1 .Lcv_sl6b
	s_waitcnt vmcnt(14)
	s_branch .Lcv_sl6j
.Lcv_sl6b:
	s_waitcnt vmcnt(20)
.Lcv_sl6j:
	v_mov_b32_e32 v8, v110
	v_mov_b32_e32 v9, v111
	v_mov_b32_e32 v10, v112
	v_mov_b32_e32 v11, v113
	v_mov_b32_e32 v12, v114
	v_mov_b32_e32 v13, v115
	v_mov_b32_e32 v14, v116
	v_mov_b32_e32 v15, v117
	s_branch .Lcv_pass
.Lcv_sl7:
	s_cmp_eq_u32 s51, 1
	s_cbranch_scc1 .Lcv_sl7b
	s_waitcnt vmcnt(7)
	s_branch .Lcv_sl7j
.Lcv_sl7b:
	s_waitcnt vmcnt(14)
.Lcv_sl7j:
	v_mov_b32_e32 v8, v118
	v_mov_b32_e32 v9, v119
	v_mov_b32_e32 v10, v120
	v_mov_b32_e32 v11, v121
	v_mov_b32_e32 v12, v122
	v_mov_b32_e32 v13, v123
	v_mov_b32_e32 v14, v124
	v_mov_b32_e32 v15, v125
	v_and_b32_e32 v14, s49, v14
	v_and_b32_e32 v15, s49, v15
	s_branch .Lcv_pass
.Lcv_done:
	s_branch .Ls5l_back
.Lnm0_entry:
	v_and_b32_e32 v134, 63, v206
	v_lshrrev_b32_e32 v135, 6, v206
	v_lshlrev_b32_e32 v132, 4, v134
	v_readfirstlane_b32 s40, v135
	s_lshl_b32 s41, s63, 3
	s_add_u32 s41, s41, s40
	s_mov_b32 s44, s16
	s_mov_b32 s45, s17
	s_mov_b32 s46, s30
	s_mov_b32 s47, s31
	s_lshl_b32 s42, s41, 12
	s_add_u32 s48, s44, s42
	s_addc_u32 s49, s45, 0
	s_add_u32 s50, s48, 0x800000
	s_addc_u32 s51, s49, 0
	s_add_u32 s52, s46, s42
	s_addc_u32 s53, s47, 0
	global_load_dwordx4 v[4:7], v132, s[48:49]
	global_load_dwordx4 v[8:11], v132, s[48:49] offset:1024
	global_load_dwordx4 v[12:15], v132, s[48:49] offset:2048
	global_load_dwordx4 v[16:19], v132, s[48:49] offset:3072
	global_load_dwordx4 v[20:23], v132, s[50:51]
	global_load_dwordx4 v[24:27], v132, s[50:51] offset:1024
	global_load_dwordx4 v[28:31], v132, s[50:51] offset:2048
	global_load_dwordx4 v[32:35], v132, s[50:51] offset:3072
	global_load_dwordx4 v[36:39], v132, s[52:53]
	global_load_dwordx4 v[40:43], v132, s[52:53] offset:1024
	global_load_dwordx4 v[44:47], v132, s[52:53] offset:2048
	global_load_dwordx4 v[48:51], v132, s[52:53] offset:3072
	v_readlane_b32 s54, v237, 11
	v_readlane_b32 s55, v237, 12
	s_lshl_b32 s42, s36, 12
	s_add_u32 s54, s54, s42
	s_addc_u32 s55, s55, 0
	global_load_dwordx4 v[52:55], v132, s[54:55]
	global_load_dwordx4 v[56:59], v132, s[54:55] offset:1024
	global_load_dwordx4 v[60:63], v132, s[54:55] offset:2048
	global_load_dwordx4 v[64:67], v132, s[54:55] offset:3072
	s_mul_i32 s42, s36, 0x12000
	s_add_u32 s42, s42, 0x2e00000
	s_add_u32 s56, s96, s42
	s_addc_u32 s57, s97, 0
	s_lshr_b32 s42, s41, 10
	s_add_u32 s42, s42, 1
	s_mul_i32 s42, s42, 0x6000
	s_add_u32 s58, s56, s42
	s_addc_u32 s59, s57, 0
	global_load_dwordx4 v[68:71], v132, s[56:57]
	global_load_dwordx4 v[72:75], v132, s[56:57] offset:1024
	global_load_dwordx4 v[76:79], v132, s[56:57] offset:2048
	global_load_dwordx4 v[80:83], v132, s[56:57] offset:3072
	s_add_u32 s56, s56, 0x1000
	s_addc_u32 s57, s57, 0
	global_load_dwordx4 v[100:103], v132, s[56:57]
	global_load_dwordx4 v[104:107], v132, s[56:57] offset:1024
	global_load_dwordx4 v[108:111], v132, s[56:57] offset:2048
	global_load_dwordx4 v[112:115], v132, s[56:57] offset:3072
	global_load_dwordx4 v[84:87], v132, s[58:59]
	global_load_dwordx4 v[88:91], v132, s[58:59] offset:1024
	global_load_dwordx4 v[92:95], v132, s[58:59] offset:2048
	global_load_dwordx4 v[96:99], v132, s[58:59] offset:3072
	s_add_u32 s58, s58, 0x1000
	s_addc_u32 s59, s59, 0
	global_load_dwordx4 v[116:119], v132, s[58:59]
	global_load_dwordx4 v[120:123], v132, s[58:59] offset:1024
	global_load_dwordx4 v[124:127], v132, s[58:59] offset:2048
	global_load_dwordx4 v[128:131], v132, s[58:59] offset:3072
	v_lshlrev_b32_e32 v137, 3, v134
	s_lshl_b32 s42, s41, 11
	s_add_u32 s42, s42, 0x2e24000
	s_add_u32 s48, s96, s42
	s_addc_u32 s49, s97, 0
	s_waitcnt vmcnt(28)
	v_mul_f32_e32 v133, v4, v4
	v_fmac_f32_e32 v133, v5, v5
	v_fmac_f32_e32 v133, v6, v6
	v_fmac_f32_e32 v133, v7, v7
	v_fmac_f32_e32 v133, v8, v8
	v_fmac_f32_e32 v133, v9, v9
	v_fmac_f32_e32 v133, v10, v10
	v_fmac_f32_e32 v133, v11, v11
	v_fmac_f32_e32 v133, v12, v12
	v_fmac_f32_e32 v133, v13, v13
	v_fmac_f32_e32 v133, v14, v14
	v_fmac_f32_e32 v133, v15, v15
	v_fmac_f32_e32 v133, v16, v16
	v_fmac_f32_e32 v133, v17, v17
	v_fmac_f32_e32 v133, v18, v18
	v_fmac_f32_e32 v133, v19, v19
	s_nop 1
	v_add_f32_dpp v133, v133, v133 row_shr:1 row_mask:0xf bank_mask:0xf bound_ctrl:0
	s_nop 1
	v_add_f32_dpp v133, v133, v133 row_shr:2 row_mask:0xf bank_mask:0xf bound_ctrl:0
	s_nop 1
	v_add_f32_dpp v133, v133, v133 row_shr:4 row_mask:0xf bank_mask:0xf bound_ctrl:0
	s_nop 1
	v_add_f32_dpp v133, v133, v133 row_shr:8 row_mask:0xf bank_mask:0xf bound_ctrl:0
	s_nop 1
	v_readlane_b32 s35, v133, 15
	v_readlane_b32 s42, v133, 31
	v_readlane_b32 s43, v133, 47
	v_readlane_b32 s54, v133, 63
	v_mov_b32_e32 v135, s35
	v_add_f32_e32 v135, s42, v135
	v_add_f32_e32 v135, s43, v135
	v_add_f32_e32 v135, s54, v135
	v_mov_b32_e32 v136, 0x358637bd
	v_fmac_f32_e32 v136, 0x3a800000, v135
	v_rsq_f32_e32 v136, v136
	s_nop 0
	s_waitcnt vmcnt(0)
	v_add_f32_e32 v100, 1.0, v100
	v_add_f32_e32 v101, 1.0, v101
	v_add_f32_e32 v102, 1.0, v102
	v_add_f32_e32 v103, 1.0, v103
	v_add_f32_e32 v104, 1.0, v104
	v_add_f32_e32 v105, 1.0, v105
	v_add_f32_e32 v106, 1.0, v106
	v_add_f32_e32 v107, 1.0, v107
	v_add_f32_e32 v108, 1.0, v108
	v_add_f32_e32 v109, 1.0, v109
	v_add_f32_e32 v110, 1.0, v110
	v_add_f32_e32 v111, 1.0, v111
	v_add_f32_e32 v112, 1.0, v112
	v_add_f32_e32 v113, 1.0, v113
	v_add_f32_e32 v114, 1.0, v114
	v_add_f32_e32 v115, 1.0, v115
	v_add_f32_e32 v116, 1.0, v116
	v_add_f32_e32 v117, 1.0, v117
	v_add_f32_e32 v118, 1.0, v118
	v_add_f32_e32 v119, 1.0, v119
	v_add_f32_e32 v120, 1.0, v120
	v_add_f32_e32 v121, 1.0, v121
	v_add_f32_e32 v122, 1.0, v122
	v_add_f32_e32 v123, 1.0, v123
	v_add_f32_e32 v124, 1.0, v124
	v_add_f32_e32 v125, 1.0, v125
	v_add_f32_e32 v126, 1.0, v126
	v_add_f32_e32 v127, 1.0, v127
	v_add_f32_e32 v128, 1.0, v128
	v_add_f32_e32 v129, 1.0, v129
	v_add_f32_e32 v130, 1.0, v130
	v_add_f32_e32 v131, 1.0, v131
	v_mul_f32_e32 v4, v4, v136
	v_mul_f32_e32 v4, v4, v52
	v_fma_f32 v4, v4, v100, v68
	v_mul_f32_e32 v5, v5, v136
	v_mul_f32_e32 v5, v5, v53
	v_fma_f32 v5, v5, v101, v69
	v_mul_f32_e32 v6, v6, v136
	v_mul_f32_e32 v6, v6, v54
	v_fma_f32 v6, v6, v102, v70
	v_mul_f32_e32 v7, v7, v136
	v_mul_f32_e32 v7, v7, v55
	v_fma_f32 v7, v7, v103, v71
	v_cvt_pk_bf16_f32 v138, v4, v5
	v_cvt_pk_bf16_f32 v139, v6, v7
	global_store_dwordx2 v137, v[138:139], s[48:49] offset:0
	v_mul_f32_e32 v8, v8, v136
	v_mul_f32_e32 v8, v8, v56
	v_fma_f32 v8, v8, v104, v72
	v_mul_f32_e32 v9, v9, v136
	v_mul_f32_e32 v9, v9, v57
	v_fma_f32 v9, v9, v105, v73
	v_mul_f32_e32 v10, v10, v136
	v_mul_f32_e32 v10, v10, v58
	v_fma_f32 v10, v10, v106, v74
	v_mul_f32_e32 v11, v11, v136
	v_mul_f32_e32 v11, v11, v59
	v_fma_f32 v11, v11, v107, v75
	v_cvt_pk_bf16_f32 v138, v8, v9
	v_cvt_pk_bf16_f32 v139, v10, v11
	global_store_dwordx2 v137, v[138:139], s[48:49] offset:512
	v_mul_f32_e32 v12, v12, v136
	v_mul_f32_e32 v12, v12, v60
	v_fma_f32 v12, v12, v108, v76
	v_mul_f32_e32 v13, v13, v136
	v_mul_f32_e32 v13, v13, v61
	v_fma_f32 v13, v13, v109, v77
	v_mul_f32_e32 v14, v14, v136
	v_mul_f32_e32 v14, v14, v62
	v_fma_f32 v14, v14, v110, v78
	v_mul_f32_e32 v15, v15, v136
	v_mul_f32_e32 v15, v15, v63
	v_fma_f32 v15, v15, v111, v79
	v_cvt_pk_bf16_f32 v138, v12, v13
	v_cvt_pk_bf16_f32 v139, v14, v15
	global_store_dwordx2 v137, v[138:139], s[48:49] offset:1024
	v_mul_f32_e32 v16, v16, v136
	v_mul_f32_e32 v16, v16, v64
	v_fma_f32 v16, v16, v112, v80
	v_mul_f32_e32 v17, v17, v136
	v_mul_f32_e32 v17, v17, v65
	v_fma_f32 v17, v17, v113, v81
	v_mul_f32_e32 v18, v18, v136
	v_mul_f32_e32 v18, v18, v66
	v_fma_f32 v18, v18, v114, v82
	v_mul_f32_e32 v19, v19, v136
	v_mul_f32_e32 v19, v19, v67
	v_fma_f32 v19, v19, v115, v83
	v_cvt_pk_bf16_f32 v138, v16, v17
	v_cvt_pk_bf16_f32 v139, v18, v19
	global_store_dwordx2 v137, v[138:139], s[48:49] offset:1536
	s_add_u32 s48, s48, 0x400000
	s_addc_u32 s49, s49, 0
	s_waitcnt vmcnt(24)
	v_mul_f32_e32 v133, v20, v20
	v_fmac_f32_e32 v133, v21, v21
	v_fmac_f32_e32 v133, v22, v22
	v_fmac_f32_e32 v133, v23, v23
	v_fmac_f32_e32 v133, v24, v24
	v_fmac_f32_e32 v133, v25, v25
	v_fmac_f32_e32 v133, v26, v26
	v_fmac_f32_e32 v133, v27, v27
	v_fmac_f32_e32 v133, v28, v28
	v_fmac_f32_e32 v133, v29, v29
	v_fmac_f32_e32 v133, v30, v30
	v_fmac_f32_e32 v133, v31, v31
	v_fmac_f32_e32 v133, v32, v32
	v_fmac_f32_e32 v133, v33, v33
	v_fmac_f32_e32 v133, v34, v34
	v_fmac_f32_e32 v133, v35, v35
	s_nop 1
	v_add_f32_dpp v133, v133, v133 row_shr:1 row_mask:0xf bank_mask:0xf bound_ctrl:0
	s_nop 1
	v_add_f32_dpp v133, v133, v133 row_shr:2 row_mask:0xf bank_mask:0xf bound_ctrl:0
	s_nop 1
	v_add_f32_dpp v133, v133, v133 row_shr:4 row_mask:0xf bank_mask:0xf bound_ctrl:0
	s_nop 1
	v_add_f32_dpp v133, v133, v133 row_shr:8 row_mask:0xf bank_mask:0xf bound_ctrl:0
	s_nop 1
	v_readlane_b32 s35, v133, 15
	v_readlane_b32 s42, v133, 31
	v_readlane_b32 s43, v133, 47
	v_readlane_b32 s54, v133, 63
	v_mov_b32_e32 v135, s35
	v_add_f32_e32 v135, s42, v135
	v_add_f32_e32 v135, s43, v135
	v_add_f32_e32 v135, s54, v135
	v_mov_b32_e32 v136, 0x358637bd
	v_fmac_f32_e32 v136, 0x3a800000, v135
	v_rsq_f32_e32 v136, v136
	s_nop 0
	v_mul_f32_e32 v20, v20, v136
	v_mul_f32_e32 v20, v20, v52
	v_fma_f32 v20, v20, v100, v68
	v_mul_f32_e32 v21, v21, v136
	v_mul_f32_e32 v21, v21, v53
	v_fma_f32 v21, v21, v101, v69
	v_mul_f32_e32 v22, v22, v136
	v_mul_f32_e32 v22, v22, v54
	v_fma_f32 v22, v22, v102, v70
	v_mul_f32_e32 v23, v23, v136
	v_mul_f32_e32 v23, v23, v55
	v_fma_f32 v23, v23, v103, v71
	v_cvt_pk_bf16_f32 v138, v20, v21
	v_cvt_pk_bf16_f32 v139, v22, v23
	global_store_dwordx2 v137, v[138:139], s[48:49] offset:0
	v_mul_f32_e32 v24, v24, v136
	v_mul_f32_e32 v24, v24, v56
	v_fma_f32 v24, v24, v104, v72
	v_mul_f32_e32 v25, v25, v136
	v_mul_f32_e32 v25, v25, v57
	v_fma_f32 v25, v25, v105, v73
	v_mul_f32_e32 v26, v26, v136
	v_mul_f32_e32 v26, v26, v58
	v_fma_f32 v26, v26, v106, v74
	v_mul_f32_e32 v27, v27, v136
	v_mul_f32_e32 v27, v27, v59
	v_fma_f32 v27, v27, v107, v75
	v_cvt_pk_bf16_f32 v138, v24, v25
	v_cvt_pk_bf16_f32 v139, v26, v27
	global_store_dwordx2 v137, v[138:139], s[48:49] offset:512
	v_mul_f32_e32 v28, v28, v136
	v_mul_f32_e32 v28, v28, v60
	v_fma_f32 v28, v28, v108, v76
	v_mul_f32_e32 v29, v29, v136
	v_mul_f32_e32 v29, v29, v61
	v_fma_f32 v29, v29, v109, v77
	v_mul_f32_e32 v30, v30, v136
	v_mul_f32_e32 v30, v30, v62
	v_fma_f32 v30, v30, v110, v78
	v_mul_f32_e32 v31, v31, v136
	v_mul_f32_e32 v31, v31, v63
	v_fma_f32 v31, v31, v111, v79
	v_cvt_pk_bf16_f32 v138, v28, v29
	v_cvt_pk_bf16_f32 v139, v30, v31
	global_store_dwordx2 v137, v[138:139], s[48:49] offset:1024
	v_mul_f32_e32 v32, v32, v136
	v_mul_f32_e32 v32, v32, v64
	v_fma_f32 v32, v32, v112, v80
	v_mul_f32_e32 v33, v33, v136
	v_mul_f32_e32 v33, v33, v65
	v_fma_f32 v33, v33, v113, v81
	v_mul_f32_e32 v34, v34, v136
	v_mul_f32_e32 v34, v34, v66
	v_fma_f32 v34, v34, v114, v82
	v_mul_f32_e32 v35, v35, v136
	v_mul_f32_e32 v35, v35, v67
	v_fma_f32 v35, v35, v115, v83
	v_cvt_pk_bf16_f32 v138, v32, v33
	v_cvt_pk_bf16_f32 v139, v34, v35
	global_store_dwordx2 v137, v[138:139], s[48:49] offset:1536
	s_add_u32 s48, s48, 0x400000
	s_addc_u32 s49, s49, 0
	s_waitcnt vmcnt(20)
	v_mul_f32_e32 v133, v36, v36
	v_fmac_f32_e32 v133, v37, v37
	v_fmac_f32_e32 v133, v38, v38
	v_fmac_f32_e32 v133, v39, v39
	v_fmac_f32_e32 v133, v40, v40
	v_fmac_f32_e32 v133, v41, v41
	v_fmac_f32_e32 v133, v42, v42
	v_fmac_f32_e32 v133, v43, v43
	v_fmac_f32_e32 v133, v44, v44
	v_fmac_f32_e32 v133, v45, v45
	v_fmac_f32_e32 v133, v46, v46
	v_fmac_f32_e32 v133, v47, v47
	v_fmac_f32_e32 v133, v48, v48
	v_fmac_f32_e32 v133, v49, v49
	v_fmac_f32_e32 v133, v50, v50
	v_fmac_f32_e32 v133, v51, v51
	s_nop 1
	v_add_f32_dpp v133, v133, v133 row_shr:1 row_mask:0xf bank_mask:0xf bound_ctrl:0
	s_nop 1
	v_add_f32_dpp v133, v133, v133 row_shr:2 row_mask:0xf bank_mask:0xf bound_ctrl:0
	s_nop 1
	v_add_f32_dpp v133, v133, v133 row_shr:4 row_mask:0xf bank_mask:0xf bound_ctrl:0
	s_nop 1
	v_add_f32_dpp v133, v133, v133 row_shr:8 row_mask:0xf bank_mask:0xf bound_ctrl:0
	s_nop 1
	v_readlane_b32 s35, v133, 15
	v_readlane_b32 s42, v133, 31
	v_readlane_b32 s43, v133, 47
	v_readlane_b32 s54, v133, 63
	v_mov_b32_e32 v135, s35
	v_add_f32_e32 v135, s42, v135
	v_add_f32_e32 v135, s43, v135
	v_add_f32_e32 v135, s54, v135
	v_mov_b32_e32 v136, 0x358637bd
	v_fmac_f32_e32 v136, 0x3a800000, v135
	v_rsq_f32_e32 v136, v136
	s_nop 0
	v_mul_f32_e32 v36, v36, v136
	v_mul_f32_e32 v36, v36, v52
	v_fma_f32 v36, v36, v116, v84
	v_mul_f32_e32 v37, v37, v136
	v_mul_f32_e32 v37, v37, v53
	v_fma_f32 v37, v37, v117, v85
	v_mul_f32_e32 v38, v38, v136
	v_mul_f32_e32 v38, v38, v54
	v_fma_f32 v38, v38, v118, v86
	v_mul_f32_e32 v39, v39, v136
	v_mul_f32_e32 v39, v39, v55
	v_fma_f32 v39, v39, v119, v87
	v_cvt_pk_bf16_f32 v138, v36, v37
	v_cvt_pk_bf16_f32 v139, v38, v39
	global_store_dwordx2 v137, v[138:139], s[48:49] offset:0
	v_mul_f32_e32 v40, v40, v136
	v_mul_f32_e32 v40, v40, v56
	v_fma_f32 v40, v40, v120, v88
	v_mul_f32_e32 v41, v41, v136
	v_mul_f32_e32 v41, v41, v57
	v_fma_f32 v41, v41, v121, v89
	v_mul_f32_e32 v42, v42, v136
	v_mul_f32_e32 v42, v42, v58
	v_fma_f32 v42, v42, v122, v90
	v_mul_f32_e32 v43, v43, v136
	v_mul_f32_e32 v43, v43, v59
	v_fma_f32 v43, v43, v123, v91
	v_cvt_pk_bf16_f32 v138, v40, v41
	v_cvt_pk_bf16_f32 v139, v42, v43
	global_store_dwordx2 v137, v[138:139], s[48:49] offset:512
	v_mul_f32_e32 v44, v44, v136
	v_mul_f32_e32 v44, v44, v60
	v_fma_f32 v44, v44, v124, v92
	v_mul_f32_e32 v45, v45, v136
	v_mul_f32_e32 v45, v45, v61
	v_fma_f32 v45, v45, v125, v93
	v_mul_f32_e32 v46, v46, v136
	v_mul_f32_e32 v46, v46, v62
	v_fma_f32 v46, v46, v126, v94
	v_mul_f32_e32 v47, v47, v136
	v_mul_f32_e32 v47, v47, v63
	v_fma_f32 v47, v47, v127, v95
	v_cvt_pk_bf16_f32 v138, v44, v45
	v_cvt_pk_bf16_f32 v139, v46, v47
	global_store_dwordx2 v137, v[138:139], s[48:49] offset:1024
	v_mul_f32_e32 v48, v48, v136
	v_mul_f32_e32 v48, v48, v64
	v_fma_f32 v48, v48, v128, v96
	v_mul_f32_e32 v49, v49, v136
	v_mul_f32_e32 v49, v49, v65
	v_fma_f32 v49, v49, v129, v97
	v_mul_f32_e32 v50, v50, v136
	v_mul_f32_e32 v50, v50, v66
	v_fma_f32 v50, v50, v130, v98
	v_mul_f32_e32 v51, v51, v136
	v_mul_f32_e32 v51, v51, v67
	v_fma_f32 v51, v51, v131, v99
	v_cvt_pk_bf16_f32 v138, v48, v49
	v_cvt_pk_bf16_f32 v139, v50, v51
	global_store_dwordx2 v137, v[138:139], s[48:49] offset:1536
	s_waitcnt vmcnt(0)
	s_branch .LBB0_854

.LBB0_642:
	s_or_b64 exec, exec, s[38:39]
	s_waitcnt lgkmcnt(0)
	s_barrier
	ds_read_b32 v0, v208
	s_movk_i32 s4, 0x2f
	s_waitcnt lgkmcnt(0)
	v_cmp_lt_i32_e32 vcc, s4, v0
	v_readfirstlane_b32 s60, v0
	s_nop 0
	s_add_u32 s99, s60, 0x630
	s_add_u32 s98, s60, 768
	s_cmp_lt_u32 s60, 48
	s_cselect_b32 s60, s99, s98
	s_cbranch_vccnz .LBB0_704
	v_readlane_b32 s44, v237, 9
	s_mul_i32 s40, s36, 0x5000
	s_lshl_b64 s[38:39], s[36:37], 12
	v_readlane_b32 s52, v237, 17
	s_mul_hi_i32 s35, s36, 0x5000
	v_readlane_b32 s53, v237, 18
	s_add_u32 s40, s52, s40
	v_readlane_b32 s54, v237, 19
	s_addc_u32 s41, s53, s35
	v_readlane_b32 s4, v235, 61
	v_readlane_b32 s55, v237, 20
	s_add_u32 s42, s54, s38
	v_readlane_b32 s5, v235, 62
	v_writelane_b32 v234, s16, 0
	s_addc_u32 s43, s55, s39
	s_lshl_b64 s[38:39], s[4:5], 2
	v_writelane_b32 v234, s17, 1
	s_mov_b32 s52, s18
	v_readlane_b32 s4, v237, 25
	v_readlane_b32 s8, v237, 29
	v_readlane_b32 s16, v237, 37
	v_readlane_b32 s17, v237, 38
	v_readlane_b32 s45, v237, 10
	v_readlane_b32 s6, v237, 27
	v_readlane_b32 s9, v237, 30
	v_readlane_b32 s16, v234, 0
	s_add_u32 s44, s8, s38
	s_mov_b32 s6, s52
	v_readlane_b32 s17, v234, 1
	s_addc_u32 s45, s9, s39
	v_readlane_b32 s46, v237, 11
	v_readlane_b32 s47, v237, 12
	v_readlane_b32 s48, v237, 13
	v_readlane_b32 s49, v237, 14
	v_readlane_b32 s50, v237, 15
	v_readlane_b32 s51, v237, 16
	v_readlane_b32 s56, v237, 21
	v_readlane_b32 s57, v237, 22
	v_readlane_b32 s58, v237, 23
	v_readlane_b32 s59, v237, 24
	v_readlane_b32 s5, v237, 26
	v_readlane_b32 s7, v237, 28
	v_readlane_b32 s10, v237, 31
	v_readlane_b32 s11, v237, 32
	v_readlane_b32 s12, v237, 33
	v_readlane_b32 s13, v237, 34
	v_readlane_b32 s14, v237, 35
	v_readlane_b32 s15, v237, 36
	v_readlane_b32 s18, v237, 39
	v_readlane_b32 s19, v237, 40
	s_branch .LBB0_646

.LBB0_645:
	s_or_b64 exec, exec, s[38:39]
	s_waitcnt lgkmcnt(0)
	s_barrier
	ds_read_b32 v0, v208
	s_movk_i32 s4, 0x2f
	s_waitcnt lgkmcnt(0)
	v_cmp_lt_i32_e32 vcc, s4, v0
	v_readfirstlane_b32 s60, v0
	s_nop 0
	s_add_u32 s99, s60, 0x630
	s_add_u32 s98, s60, 768
	s_cmp_lt_u32 s60, 48
	s_cselect_b32 s60, s99, s98
	s_cbranch_vccnz .LBB0_704
